# main G1 epilogue skips its vmcnt(0) drain unless the tile issued lower-bound loads (type-5 tiles)
# baseline (speedup 1.0000x reference)
.LBB0_79:
	s_or_b64 exec, exec, s[0:1]
	v_cmp_lt_i32_e64 s[0:1], -1, v0
	s_mov_b64 s[20:21], -1
	s_or_b64 vcc, s[6:7], s[8:9]
	s_cbranch_vccz .Lg1_epi_nowait
	s_waitcnt vmcnt(0)
.Lg1_epi_nowait:
	s_cmp_gt_i32 s93, 4
	v_pk_add_f32 v[172:173], v[38:39], 1.0 op_sel_hi:[1,0] neg_lo:[1,0] neg_hi:[1,0]
	s_cbranch_scc0 .LBB0_81
	v_mul_f32_e32 v147, 0xbfb8aa3b, v142
	v_exp_f32_e32 v148, v147
	v_mul_f32_e32 v147, 0xbfb8aa3b, v138
	v_exp_f32_e32 v150, v147
	v_pk_add_f32 v[184:185], v[40:41], 1.0 op_sel_hi:[1,0] neg_lo:[1,0] neg_hi:[1,0]
	v_add_f32_e32 v147, 1.0, v148
	v_rcp_f32_e32 v152, v147
	v_mul_f32_e32 v147, 0xbfb8aa3b, v143
	v_exp_f32_e32 v149, v147
	v_mul_f32_e32 v147, 0xbfb8aa3b, v139
	v_add_f32_e32 v153, 1.0, v150
	v_exp_f32_e32 v151, v147
	v_add_f32_e32 v147, 1.0, v149
	v_rcp_f32_e32 v178, v153
	v_rcp_f32_e32 v153, v147
	v_pk_mul_f32 v[148:149], v[148:149], v[172:173]
	v_add_f32_e32 v147, 1.0, v151
	v_rcp_f32_e32 v179, v147
	v_pk_mul_f32 v[148:149], v[152:153], v[148:149]
	v_pk_fma_f32 v[152:153], v[152:153], v[172:173], v[38:39]
	v_cmp_ge_f32_e32 vcc, 0.5, v148
	v_mul_f32_e32 v147, 0xbfb8aa3b, v144
	s_mov_b64 s[20:21], 0
	v_cndmask_b32_e64 v182, -v152, v148, vcc
	v_cmp_ge_f32_e32 vcc, 0.5, v149
	s_nop 1
	v_cndmask_b32_e64 v183, -v153, v149, vcc
	v_pk_add_f32 v[148:149], v[34:35], 1.0 op_sel_hi:[1,0] neg_lo:[1,0] neg_hi:[1,0]
	s_nop 0
	v_pk_mul_f32 v[150:151], v[150:151], v[148:149]
	v_pk_fma_f32 v[148:149], v[178:179], v[148:149], v[34:35]
	v_pk_mul_f32 v[150:151], v[178:179], v[150:151]
	s_nop 0
	v_cmp_ge_f32_e32 vcc, 0.5, v150
	s_nop 1
	v_cndmask_b32_e64 v186, -v148, v150, vcc
	v_exp_f32_e32 v148, v147
	v_mul_f32_e32 v147, 0xbfb8aa3b, v140
	v_cmp_ge_f32_e32 vcc, 0.5, v151
	v_exp_f32_e32 v150, v147
	v_add_f32_e32 v147, 1.0, v148
	v_cndmask_b32_e64 v187, -v149, v151, vcc
	v_mul_f32_e32 v149, 0xbfb8aa3b, v145
	v_exp_f32_e32 v149, v149
	v_rcp_f32_e32 v152, v147
	v_add_f32_e32 v147, 1.0, v150
	v_mul_f32_e32 v151, 0xbfb8aa3b, v141
	v_rcp_f32_e32 v178, v147
	v_add_f32_e32 v147, 1.0, v149
	v_exp_f32_e32 v151, v151
	v_rcp_f32_e32 v153, v147
	v_pk_mul_f32 v[148:149], v[148:149], v[184:185]
	v_add_f32_e32 v147, 1.0, v151
	v_pk_mul_f32 v[148:149], v[152:153], v[148:149]
	v_rcp_f32_e32 v179, v147
	v_pk_fma_f32 v[152:153], v[152:153], v[184:185], v[40:41]
	v_cmp_ge_f32_e32 vcc, 0.5, v148
	s_nop 1
	v_cndmask_b32_e64 v184, -v152, v148, vcc
	v_cmp_ge_f32_e32 vcc, 0.5, v149
	s_nop 1
	v_cndmask_b32_e64 v185, -v153, v149, vcc
	v_pk_add_f32 v[148:149], v[36:37], 1.0 op_sel_hi:[1,0] neg_lo:[1,0] neg_hi:[1,0]
	s_nop 0
	v_pk_mul_f32 v[150:151], v[150:151], v[148:149]
	v_pk_fma_f32 v[148:149], v[178:179], v[148:149], v[36:37]
	v_pk_mul_f32 v[150:151], v[178:179], v[150:151]
	s_nop 0
	v_cmp_ge_f32_e32 vcc, 0.5, v150
	s_nop 1
	v_cndmask_b32_e64 v188, -v148, v150, vcc
	v_cmp_ge_f32_e32 vcc, 0.5, v151
	s_nop 1
	v_cndmask_b32_e64 v189, -v149, v151, vcc
